# FFN-up epilogue: conv-weight loads issued with the row-stat loads (one wait instead of two); group-2 weight wait moved ahead of the stores
# speedup vs baseline: 1.0081x; 1.0081x over previous
;     __device__ __forceinline__ void operator()(f32x4 (&acc)[2][2][4][2], const Unit& u, int wr, int wc, int fr, int fq) const {
;     ...
;         for (int i = 0; i < 8; ++i) { const int tok = u.pm * 248 + 62 * (2 * (i >> 2) + wr) - 1 + 16 * (i & 3) + fr; int tc = tok < 0 ? 0 : tok; tc = tc > ntok - 1 ? ntok - 1 : tc;
;             qs[i] = *(const f32x4*)(ss + (size_t)tc * 4); }
;         asm volatile("" : "+v"(qs[0]), "+v"(qs[1]), "+v"(qs[2]), "+v"(qs[3]), "+v"(qs[4]), "+v"(qs[5]), "+v"(qs[6]), "+v"(qs[7]));
; #pragma unroll
;         for (int ai = 0; ai < 2; ++ai) {
; #pragma unroll
;             for (int m = 0; m < 4; ++m) {
;                 const f32x4 q = qs[ai * 4 + m];
;                 const float rs = rsqrtf(((q[0] + q[1]) + (q[2] + q[3])) * (1.f / DM) + EPS);
; #pragma unroll
;                 for (int bj = 0; bj < 2; ++bj)
; #pragma unroll
;                     for (int n = 0; n < 2; ++n) acc[ai][bj][m][n] *= rs;
;             }
;         }
;         __builtin_amdgcn_sched_barrier(0); asm volatile("s_nop 1");
;         const bool f15 = fr == 15, f0 = fr == 0;
;         f32x2 wq[2][2][4];
;     ...
;         CONV_WLOAD(0, 0, 0);
; #pragma unroll
;         for (int n = 0; n < 2; ++n) {
;             unsigned stash[2][4];
; #pragma unroll
;             for (int jh = 0; jh < 2; ++jh) {
;                 const int g_ = 2 * n + jh, cb_ = g_ & 1;
;                 if (g_ + 1 < 4) CONV_WLOAD(cb_ ^ 1, (g_ + 1) >> 1, (g_ + 1) & 1);
;                 f32x2 w0[2], w1[2], w2[2], bb[2], w0f[2], w2l[2];
; #pragma unroll
;                 for (int bj = 0; bj < 2; ++bj) { w0[bj] = wq[cb_][bj][0]; w1[bj] = wq[cb_][bj][1]; w2[bj] = wq[cb_][bj][2]; bb[bj] = wq[cb_][bj][3];
;                     w0f[bj] = f0 ? w0[bj] : (f32x2){0.f, 0.f}; w2l[bj] = f15 ? w2[bj] : (f32x2){0.f, 0.f}; }
; #pragma unroll
;                 for (int ai = 0; ai < 2; ++ai) {
;                     const int tokbase = u.pm * 248 + 62 * (2 * ai + wr) - 1;
; #pragma unroll
;                     for (int m = 0; m < 4; ++m) {
;                         const int rr = 16 * m + fr, tok = tokbase + rr, pos = tok & Tmask;
;                         const bool lbad = pos == 0, rbad = pos == Tmask;
;                         float uu[2][2];
; #pragma unroll
;                         for (int bj = 0; bj < 2; ++bj) {
.LBB0_789:
	s_mul_i32 s15, s31, 0xf8
	s_add_i32 s15, s15, -1
	v_add_u32_e32 v102, s15, v17
	v_add_u32_e32 v104, 16, v102
	v_add_u32_e32 v105, s1, v104
	v_med3_i32 v105, v105, 0, v242
	v_add_u32_e32 v104, s38, v104
	v_lshlrev_b32_e32 v106, 4, v105
	v_add_u32_e32 v105, 32, v102
	v_med3_i32 v104, v104, 0, v242
	v_lshlrev_b32_e32 v110, 4, v104
	v_add_u32_e32 v104, s38, v105
	s_ashr_i32 s21, s20, 31
	v_add_u32_e32 v108, 48, v102
	v_med3_i32 v104, v104, 0, v242
	s_lshl_b64 s[6:7], s[20:21], 12
	v_add_u32_e32 v103, s1, v102
	v_add_u32_e32 v107, s1, v105
	v_add_u32_e32 v109, s1, v108
	v_add_u32_e32 v102, s38, v102
	v_lshlrev_b32_e32 v111, 4, v104
	v_add_u32_e32 v104, s38, v108
	v_med3_i32 v103, v103, 0, v242
	v_med3_i32 v107, v107, 0, v242
	v_med3_i32 v109, v109, 0, v242
	v_med3_i32 v102, v102, 0, v242
	v_med3_i32 v104, v104, 0, v242
	v_lshl_add_u64 v[214:215], v[194:195], 0, s[6:7]
	v_readlane_b32 s6, v253, 24
	v_lshlrev_b32_e32 v103, 4, v103
	v_lshlrev_b32_e32 v107, 4, v107
	v_lshlrev_b32_e32 v109, 4, v109
	v_lshlrev_b32_e32 v102, 4, v102
	v_lshlrev_b32_e32 v108, 4, v104
	v_readlane_b32 s7, v253, 25
	s_nop 4
	global_load_dwordx4 v[174:177], v102, s[6:7]
	s_nop 0
	global_load_dwordx4 v[216:219], v103, s[6:7]
	s_nop 0
	global_load_dwordx4 v[166:169], v108, s[6:7]
	global_load_dwordx4 v[170:173], v111, s[6:7]
	global_load_dwordx4 v[178:181], v110, s[6:7]
	global_load_dwordx4 v[182:185], v109, s[6:7]
	global_load_dwordx4 v[186:189], v107, s[6:7]
	s_nop 0
	global_load_dwordx4 v[220:223], v106, s[6:7]
	global_load_dwordx4 v[114:117], v[214:215], off offset:1024
	global_load_dwordx4 v[110:113], v[214:215], off offset:3072
	global_load_dwordx4 v[130:133], v[214:215], off offset:512
	global_load_dwordx4 v[102:105], v[214:215], off offset:1536
	global_load_dwordx4 v[126:129], v[214:215], off offset:2560
	global_load_dwordx4 v[106:109], v[214:215], off offset:3584
	global_load_dwordx4 v[122:125], v[214:215], off
	global_load_dwordx4 v[118:121], v[214:215], off offset:2048
	s_waitcnt vmcnt(8)
	s_nop 0
	v_mov_b32_e32 v208, v217
	v_mov_b32_e32 v209, v218
	v_mov_b32_e32 v217, v219
	v_mov_b32_e32 v218, v221
	v_mov_b32_e32 v219, v222
	v_mov_b32_e32 v221, v223
	v_pk_add_f32 v[216:217], v[208:209], v[216:217]
	v_pk_add_f32 v[218:219], v[218:219], v[220:221]
	v_mov_b32_e32 v221, v216
	v_mov_b32_e32 v220, v218
	v_mov_b32_e32 v216, v219
	v_pk_add_f32 v[216:217], v[220:221], v[216:217]
	s_nop 0
	v_pk_fma_f32 v[216:217], v[216:217], s[60:61], v[202:203] op_sel_hi:[1,0,0]
	s_nop 0
	v_mul_f32_e32 v218, 0x4b800000, v217
	v_cmp_gt_f32_e64 s[6:7], s59, v217
	v_cmp_gt_f32_e32 vcc, s59, v216
	s_nop 0
	v_cndmask_b32_e64 v217, v217, v218, s[6:7]
	v_rsq_f32_e32 v217, v217
	s_nop 0
	v_mul_f32_e32 v218, 0x45800000, v217
	v_cndmask_b32_e64 v212, v217, v218, s[6:7]
	v_mul_f32_e32 v217, 0x4b800000, v216
	v_cndmask_b32_e32 v216, v216, v217, vcc
	v_rsq_f32_e32 v216, v216
	v_pk_mul_f32 v[224:225], v[154:155], v[212:213] op_sel_hi:[1,0]
	v_pk_mul_f32 v[228:229], v[162:163], v[212:213] op_sel_hi:[1,0]
	v_mul_f32_e32 v217, 0x45800000, v216
	v_cndmask_b32_e32 v154, v216, v217, vcc
	v_pk_mul_f32 v[162:163], v[158:159], v[154:155] op_sel_hi:[1,0]
	v_pk_mul_f32 v[158:159], v[150:151], v[154:155] op_sel_hi:[1,0]
	s_nop 1
	s_add_i32 s21, s15, s1
	v_add_u32_e32 v249, s21, v17
	v_and_b32_e32 v150, s35, v249
	v_cmp_eq_u32_e64 s[80:81], s35, v150
	v_cmp_eq_u32_e64 s[82:83], 0, v150
	s_or_b64 s[6:7], s[82:83], s[80:81]
	s_mov_b64 vcc, s[6:7]
	s_waitcnt vmcnt(7)
	v_cndmask_b32_e64 v251, 0, v115, s[42:43]
	v_cndmask_b32_e64 v234, 0, v114, s[42:43]
	s_waitcnt vmcnt(6)
	v_cndmask_b32_e64 v151, 0, v111, s[42:43]
	s_waitcnt vmcnt(4)
	v_fma_f32 v220, v130, v228, v102
	v_fma_f32 v221, v131, v229, v103
	s_waitcnt vmcnt(2)
	v_fma_f32 v222, v126, v224, v106
	v_fma_f32 v223, v127, v225, v107
	s_waitcnt vmcnt(1)
	v_fmac_f32_dpp v220, v228, v122 row_shr:1 row_mask:0xf bank_mask:0xf bound_ctrl:0
	v_fmac_f32_dpp v221, v229, v123 row_shr:1 row_mask:0xf bank_mask:0xf bound_ctrl:0
	s_waitcnt vmcnt(0)
	v_fmac_f32_dpp v222, v224, v118 row_shr:1 row_mask:0xf bank_mask:0xf bound_ctrl:0
	v_fmac_f32_dpp v223, v225, v119 row_shr:1 row_mask:0xf bank_mask:0xf bound_ctrl:0
	v_cndmask_b32_e64 v213, 0, v110, s[42:43]
	v_fmac_f32_dpp v220, v228, v114 row_shl:1 row_mask:0xf bank_mask:0xf bound_ctrl:0
	v_fmac_f32_dpp v221, v229, v115 row_shl:1 row_mask:0xf bank_mask:0xf bound_ctrl:0
	v_fmac_f32_dpp v222, v224, v110 row_shl:1 row_mask:0xf bank_mask:0xf bound_ctrl:0
	v_fmac_f32_dpp v223, v225, v111 row_shl:1 row_mask:0xf bank_mask:0xf bound_ctrl:0
	s_nop 0
	v_fmac_f32_dpp v220, v162, v234 row_ror:15 row_mask:0xf bank_mask:0xf bound_ctrl:0
	v_fmac_f32_dpp v221, v163, v251 row_ror:15 row_mask:0xf bank_mask:0xf bound_ctrl:0
	v_fmac_f32_dpp v222, v158, v213 row_ror:15 row_mask:0xf bank_mask:0xf bound_ctrl:0
	v_fmac_f32_dpp v223, v159, v151 row_ror:15 row_mask:0xf bank_mask:0xf bound_ctrl:0
	s_cbranch_vccz .LBB0_791
	v_cndmask_b32_e64 v150, v228, v162, s[44:45]
	v_mov_b32_e32 v216, v1
	v_mov_b32_e32 v208, v1
	v_mov_b32_e32 v209, v1
	v_mov_b32_dpp v216, v150 row_ror:15 row_mask:0xf bank_mask:0xf
	v_cndmask_b32_e64 v150, v229, v163, s[44:45]
	v_mov_b32_e32 v217, v1
	v_mov_b32_dpp v208, v228 row_ror:1 row_mask:0xf bank_mask:0xf
	v_mov_b32_dpp v209, v229 row_ror:1 row_mask:0xf bank_mask:0xf
	v_mov_b32_dpp v217, v150 row_ror:15 row_mask:0xf bank_mask:0xf
	v_pk_mul_f32 v[208:209], v[122:123], v[208:209]
	v_pk_mul_f32 v[216:217], v[114:115], v[216:217]
	v_cndmask_b32_e64 v209, 0, v209, s[82:83]
	v_cndmask_b32_e64 v208, 0, v208, s[82:83]
	v_cndmask_b32_e64 v217, 0, v217, s[80:81]
	v_cndmask_b32_e64 v216, 0, v216, s[80:81]
	v_pk_add_f32 v[208:209], v[208:209], v[216:217]
	v_cndmask_b32_e64 v150, v224, v158, s[44:45]
	v_mov_b32_e32 v216, v1
	v_pk_add_f32 v[220:221], v[220:221], v[208:209] neg_lo:[0,1] neg_hi:[0,1]
	v_mov_b32_e32 v208, v1
	v_mov_b32_dpp v216, v150 row_ror:15 row_mask:0xf bank_mask:0xf
	v_mov_b32_e32 v209, v1
	v_cndmask_b32_e64 v150, v225, v159, s[44:45]
	v_mov_b32_e32 v217, v1
	v_mov_b32_dpp v208, v224 row_ror:1 row_mask:0xf bank_mask:0xf
	v_mov_b32_dpp v209, v225 row_ror:1 row_mask:0xf bank_mask:0xf
	v_mov_b32_dpp v217, v150 row_ror:15 row_mask:0xf bank_mask:0xf
	v_pk_mul_f32 v[208:209], v[118:119], v[208:209]
	v_pk_mul_f32 v[216:217], v[110:111], v[216:217]
	v_cndmask_b32_e64 v209, 0, v209, s[82:83]
	v_cndmask_b32_e64 v208, 0, v208, s[82:83]
	v_cndmask_b32_e64 v217, 0, v217, s[80:81]
	v_cndmask_b32_e64 v216, 0, v216, s[80:81]
	v_pk_add_f32 v[208:209], v[208:209], v[216:217]
	s_nop 0
	v_pk_add_f32 v[222:223], v[222:223], v[208:209] neg_lo:[0,1] neg_hi:[0,1]

; __device__ __forceinline__ unsigned cvtpk(float lo, float hi) { f32x2_t v = {lo, hi}; bf16x2_t b = __builtin_convertvector(v, bf16x2_t); return __builtin_bit_cast(unsigned, b); }
;     __device__ __forceinline__ void operator()(f32x4 (&acc)[2][2][4][2], const Unit& u, int wr, int wc, int fr, int fq) const {
;     ...
;                         float a[2];
; #pragma unroll
;                         for (int jj = 0; jj < 2; ++jj) { const float g = uu[0][jj]; a[jj] = g * uu[1][jj] * __builtin_amdgcn_rcpf(1.f + __builtin_amdgcn_exp2f(-g * LOG2E)); }
;                         const unsigned pk = cvtpk(a[0], a[1]);
;                         if (jh == 0) stash[ai][m] = pk;
;                         else if (rr >= 1 && rr <= 62 && tok < ntok) { u32x2 w; w.x = stash[ai][m]; w.y = pk; *(u32x2*)(obase + (size_t)tok * FFN + 4 * n) = w; }
.LBB0_807:
	s_lshl_b32 s6, s20, 7
	s_ashr_i32 s7, s6, 31
	v_lshl_add_u64 v[78:79], s[6:7], 1, v[196:197]
	v_readlane_b32 s6, v255, 21
	v_cmp_gt_i32_e32 vcc, s31, v249
	v_readlane_b32 s7, v255, 22
	s_and_b64 s[40:41], s[6:7], vcc
	s_waitcnt vmcnt(0)
	s_and_saveexec_b64 s[6:7], s[40:41]
	s_cbranch_execz .LBB0_809
	v_mul_f32_e32 v87, 0xbfb8aa3b, v220
	v_exp_f32_e32 v87, v87
	v_pk_mul_f32 v[160:161], v[160:161], v[152:153]
	v_pk_mul_f32 v[180:181], v[222:223], v[220:221]
	s_movk_i32 s15, 0x1600
	v_add_f32_e32 v87, 1.0, v87
	v_rcp_f32_e32 v172, v87
	v_mul_f32_e32 v87, 0xbfb8aa3b, v221
	v_exp_f32_e32 v87, v87
	s_nop 0
	v_add_f32_e32 v87, 1.0, v87
	v_rcp_f32_e32 v173, v87
	v_mul_f32_e32 v87, 0xbfb8aa3b, v152
	v_exp_f32_e32 v87, v87
	v_pk_mul_f32 v[172:173], v[180:181], v[172:173]
	s_nop 0
	v_cvt_pk_bf16_f32 v172, v172, v173
	v_add_f32_e32 v87, 1.0, v87
	v_rcp_f32_e32 v152, v87
	v_mul_f32_e32 v87, 0xbfb8aa3b, v153
	v_exp_f32_e32 v87, v87
	s_nop 0
	v_add_f32_e32 v87, 1.0, v87
	v_rcp_f32_e32 v153, v87
	s_nop 0
	v_pk_mul_f32 v[152:153], v[160:161], v[152:153]
	s_nop 0
	v_cvt_pk_bf16_f32 v173, v152, v153
	v_mad_i64_i32 v[152:153], s[20:21], v249, s15, v[78:79]
	global_store_dwordx2 v[152:153], v[172:173], off

;     __device__ __forceinline__ void operator()(f32x4 (&acc)[2][2][4][2], const Unit& u, int wr, int wc, int fr, int fq) const {
;     ...
;         CONV_WLOAD(0, 0, 0);
; #pragma unroll
;         for (int n = 0; n < 2; ++n) {
;             unsigned stash[2][4];
; #pragma unroll
;             for (int jh = 0; jh < 2; ++jh) {
;                 const int g_ = 2 * n + jh, cb_ = g_ & 1;
;                 if (g_ + 1 < 4) CONV_WLOAD(cb_ ^ 1, (g_ + 1) >> 1, (g_ + 1) & 1);
;                 f32x2 w0[2], w1[2], w2[2], bb[2], w0f[2], w2l[2];
; #pragma unroll
;                 for (int bj = 0; bj < 2; ++bj) { w0[bj] = wq[cb_][bj][0]; w1[bj] = wq[cb_][bj][1]; w2[bj] = wq[cb_][bj][2]; bb[bj] = wq[cb_][bj][3];
;                     w0f[bj] = f0 ? w0[bj] : (f32x2){0.f, 0.f}; w2l[bj] = f15 ? w2[bj] : (f32x2){0.f, 0.f}; }
; #pragma unroll
;                 for (int ai = 0; ai < 2; ++ai) {
;                     const int tokbase = u.pm * 248 + 62 * (2 * ai + wr) - 1;
; #pragma unroll
;                     for (int m = 0; m < 4; ++m) {
;                         const int rr = 16 * m + fr, tok = tokbase + rr, pos = tok & Tmask;
;                         const bool lbad = pos == 0, rbad = pos == Tmask;
;                         float uu[2][2];
; #pragma unroll
;                         for (int bj = 0; bj < 2; ++bj) {
;                             const f32x4 c = acc[ai][bj][m][n], cm = acc[ai][bj][m > 0 ? m - 1 : m][n], cp = acc[ai][bj][m < 3 ? m + 1 : m][n];
; #pragma unroll
;                             for (int jj = 0; jj < 2; ++jj) {
;                                 const int j = 2 * jh + jj;
;                                 float t = bb[bj][jj] + w1[bj][jj] * c[j];
;                                 fmac_shr1(t, c[j], w0[bj][jj]);
;                                 fmac_shl1(t, c[j], w2[bj][jj]);
;                                 if (m > 0) fmac_ror1(t, cm[j], w0f[bj][jj]);
;                                 if (m < 3) fmac_ror15(t, cp[j], w2l[bj][jj]);
;                                 uu[bj][jj] = t;
;                             }
;                         }
;                         if (__any(lbad | rbad)) {
.LBB0_837:
	s_or_b64 exec, exec, s[92:93]
	v_mov_b32_e32 v213, v212
	v_mov_b32_e32 v155, v154
	v_pk_mul_f32 v[120:121], v[66:67], v[212:213]
	v_pk_mul_f32 v[118:119], v[58:59], v[212:213]
	v_pk_mul_f32 v[112:113], v[62:63], v[154:155]
	v_pk_mul_f32 v[104:105], v[54:55], v[154:155]
	global_load_dwordx2 v[76:77], v[214:215], off offset:24
	global_load_dwordx2 v[84:85], v[214:215], off offset:536
	global_load_dwordx2 v[72:73], v[214:215], off offset:1048
	global_load_dwordx2 v[54:55], v[214:215], off offset:1560
	global_load_dwordx2 v[66:67], v[214:215], off offset:2072
	global_load_dwordx2 v[80:81], v[214:215], off offset:2584
	global_load_dwordx2 v[62:63], v[214:215], off offset:3096
	global_load_dwordx2 v[58:59], v[214:215], off offset:3608
	v_fma_f32 v96, v120, v114, v70
	v_fma_f32 v97, v121, v115, v71
	v_fma_f32 v100, v118, v110, v74
	v_fma_f32 v101, v119, v111, v75
	v_fmac_f32_dpp v96, v120, v102 row_shr:1 row_mask:0xf bank_mask:0xf bound_ctrl:0
	v_fmac_f32_dpp v97, v121, v103 row_shr:1 row_mask:0xf bank_mask:0xf bound_ctrl:0
	v_fmac_f32_dpp v100, v118, v94 row_shr:1 row_mask:0xf bank_mask:0xf bound_ctrl:0
	v_fmac_f32_dpp v101, v119, v95 row_shr:1 row_mask:0xf bank_mask:0xf bound_ctrl:0
	v_cndmask_b32_e64 v129, 0, v107, s[42:43]
	v_cndmask_b32_e64 v131, 0, v106, s[42:43]
	v_cndmask_b32_e64 v125, 0, v99, s[42:43]
	v_cndmask_b32_e64 v128, 0, v98, s[42:43]
	v_fmac_f32_dpp v96, v120, v106 row_shl:1 row_mask:0xf bank_mask:0xf bound_ctrl:0
	v_fmac_f32_dpp v97, v121, v107 row_shl:1 row_mask:0xf bank_mask:0xf bound_ctrl:0
	v_fmac_f32_dpp v100, v118, v98 row_shl:1 row_mask:0xf bank_mask:0xf bound_ctrl:0
	v_fmac_f32_dpp v101, v119, v99 row_shl:1 row_mask:0xf bank_mask:0xf bound_ctrl:0
	v_cmp_ne_u32_e32 vcc, 0, v167
	v_fmac_f32_dpp v96, v112, v131 row_ror:15 row_mask:0xf bank_mask:0xf bound_ctrl:0
	v_fmac_f32_dpp v97, v113, v129 row_ror:15 row_mask:0xf bank_mask:0xf bound_ctrl:0
	v_fmac_f32_dpp v100, v104, v128 row_ror:15 row_mask:0xf bank_mask:0xf bound_ctrl:0
	v_fmac_f32_dpp v101, v105, v125 row_ror:15 row_mask:0xf bank_mask:0xf bound_ctrl:0
	s_cbranch_vccz .LBB0_839
	v_cndmask_b32_e64 v83, v120, v112, s[44:45]
	v_mov_b32_e32 v89, v1
	v_mov_b32_e32 v108, v1
	v_mov_b32_e32 v109, v1
	v_mov_b32_dpp v89, v83 row_ror:15 row_mask:0xf bank_mask:0xf
	v_cndmask_b32_e64 v83, v121, v113, s[44:45]
	v_mov_b32_e32 v88, v1
	v_mov_b32_dpp v108, v121 row_ror:1 row_mask:0xf bank_mask:0xf
	v_mov_b32_dpp v109, v83 row_ror:15 row_mask:0xf bank_mask:0xf
	v_mov_b32_e32 v116, v103
	v_mov_b32_e32 v117, v107
	v_mov_b32_dpp v88, v120 row_ror:1 row_mask:0xf bank_mask:0xf
	v_mov_b32_e32 v92, v102
	v_mov_b32_e32 v93, v106
	v_pk_mul_f32 v[108:109], v[116:117], v[108:109]
	v_pk_mul_f32 v[88:89], v[92:93], v[88:89]
	v_cndmask_b32_e64 v93, 0, v109, s[80:81]
	v_cndmask_b32_e64 v83, v118, v104, s[44:45]
	v_mov_b32_e32 v109, v1
	v_cndmask_b32_e64 v92, 0, v89, s[80:81]
	v_cndmask_b32_e64 v89, 0, v108, s[82:83]
	v_mov_b32_e32 v108, v1
	v_mov_b32_dpp v109, v83 row_ror:15 row_mask:0xf bank_mask:0xf
	v_mov_b32_e32 v126, v1
	v_cndmask_b32_e64 v83, v119, v105, s[44:45]
	v_mov_b32_e32 v127, v1
	v_mov_b32_dpp v108, v118 row_ror:1 row_mask:0xf bank_mask:0xf
	v_mov_b32_e32 v116, v94
	v_mov_b32_e32 v117, v98
	v_mov_b32_dpp v126, v119 row_ror:1 row_mask:0xf bank_mask:0xf
	v_mov_b32_dpp v127, v83 row_ror:15 row_mask:0xf bank_mask:0xf
	v_mov_b32_e32 v132, v95
	v_mov_b32_e32 v133, v99
	v_cndmask_b32_e64 v88, 0, v88, s[82:83]
	v_pk_mul_f32 v[108:109], v[116:117], v[108:109]
	v_pk_mul_f32 v[126:127], v[132:133], v[126:127]
	v_cndmask_b32_e64 v116, 0, v109, s[80:81]
	v_cndmask_b32_e64 v108, 0, v108, s[82:83]
	v_cndmask_b32_e64 v117, 0, v127, s[80:81]
	v_cndmask_b32_e64 v109, 0, v126, s[82:83]
	v_pk_add_f32 v[88:89], v[88:89], v[92:93]
	s_nop 0
	v_pk_add_f32 v[96:97], v[96:97], v[88:89] neg_lo:[0,1] neg_hi:[0,1]
	v_pk_add_f32 v[88:89], v[108:109], v[116:117]
	s_nop 0
	v_pk_add_f32 v[100:101], v[100:101], v[88:89] neg_lo:[0,1] neg_hi:[0,1]
